# P1 full-line stores + sample QK batched reads + LRU gate MFMA: fragment reads batched two blocks ahead with counted waits
# speedup vs baseline: 1.0125x; 1.0125x over previous
; #define LAS __attribute__((address_space(3)))
; __device__ __forceinline__ float sigm(float v) { return __builtin_amdgcn_rcpf(1.f + __builtin_amdgcn_exp2f(-LOG2E * v)); }
; __device__ __forceinline__ void lru_unit(Frame& F, int seq, int n) {
;     ...
; #pragma unroll
;             for (int tt = 0; tt < 4; ++tt)
; #pragma unroll
;                 for (int kk = 0; kk < 4; ++kk) {
;                     const bf16x8 af = *(const LAS bf16x8*)(XCB + (16 * tt + (lane & 15)) * 136 + 32 * kk + 8 * tq);
;                     ar[tt] = __builtin_amdgcn_mfma_f32_16x16x32_bf16(af, Br[kk], ar[tt], 0, 0, 0);
;                     ai_[tt] = __builtin_amdgcn_mfma_f32_16x16x32_bf16(af, Bi[kk], ai_[tt], 0, 0, 0);
;                 }
;             float A[4][4], B[4][4];
; #pragma unroll
;             for (int tt = 0; tt < 4; ++tt)
; #pragma unroll
;                 for (int rg = 0; rg < 4; ++rg) {
;                     const int t = 16 * tt + 4 * tq + rg;
;                     const float r = sigm(ar[tt][rg] + brg), ig = sigm(ai_[tt][rg] + big);
;                     const float av = __builtin_amdgcn_exp2f(r * nsp);
;                     float mult = __builtin_amdgcn_sqrtf(fmaxf(__builtin_fmaf(-av, av, 1.f), 0.f));
;                     if (!smp && (t0 + t) == 0) mult = 1.f;
;                     A[tt][rg] = av; B[tt][rg] = mult * ig * BB[t * 132 + dl];
.LBB0_440:
	s_or_b64 exec, exec, s[46:47]
	s_waitcnt lgkmcnt(0)
	s_barrier
	s_nop 0
	s_nop 0
	s_nop 0
	ds_read_b128 v[220:223], v170 offset:0
	ds_read_b128 v[224:227], v170 offset:64
	ds_read_b128 v[228:231], v170 offset:128
	ds_read_b128 v[232:235], v170 offset:192
	ds_read_b128 v[236:239], v170 offset:4352
	ds_read_b128 v[240:243], v170 offset:4416
	ds_read_b128 v[244:247], v170 offset:4480
	ds_read_b128 v[248:251], v170 offset:4544
	s_waitcnt lgkmcnt(7)
	v_mfma_f32_16x16x32_bf16 v[86:89], v[220:223], v[42:45], 0
	s_nop 0
	v_mfma_f32_16x16x32_bf16 v[82:85], v[220:223], v[66:69], 0
	s_nop 0
	s_waitcnt lgkmcnt(6)
	v_mfma_f32_16x16x32_bf16 v[86:89], v[224:227], v[46:49], v[86:89]
	v_mfma_f32_16x16x32_bf16 v[82:85], v[224:227], v[50:53], v[82:85]
	s_nop 0
	s_nop 0
	s_waitcnt lgkmcnt(5)
	v_mfma_f32_16x16x32_bf16 v[86:89], v[228:231], v[58:61], v[86:89]
	v_mfma_f32_16x16x32_bf16 v[82:85], v[228:231], v[54:57], v[82:85]
	s_nop 0
	s_nop 0
	s_waitcnt lgkmcnt(4)
	v_mfma_f32_16x16x32_bf16 v[106:109], v[232:235], v[70:73], v[82:85]
	s_nop 4
	s_nop 0
	s_nop 1
	v_add_f32_e32 v106, v144, v106
	v_mfma_f32_16x16x32_bf16 v[110:113], v[232:235], v[62:65], v[86:89]
	ds_read_b128 v[220:223], v170 offset:8704
	ds_read_b128 v[224:227], v170 offset:8768
	ds_read_b128 v[228:231], v170 offset:8832
	ds_read_b128 v[232:235], v170 offset:8896
	s_nop 0
	v_mul_f32_e32 v106, 0xbfb8aa3b, v106
	v_exp_f32_e32 v106, v106
	s_nop 0
	s_waitcnt lgkmcnt(7)
	v_mfma_f32_16x16x32_bf16 v[86:89], v[236:239], v[42:45], 0
	v_add_f32_e32 v107, v144, v107
	s_nop 1
	v_add_f32_e32 v110, v143, v110
	v_mul_f32_e32 v110, 0xbfb8aa3b, v110
	v_mfma_f32_16x16x32_bf16 v[82:85], v[236:239], v[66:69], 0
	v_exp_f32_e32 v110, v110
	v_add_f32_e32 v106, 1.0, v106
	v_rcp_f32_e32 v106, v106
	s_nop 0
	s_waitcnt lgkmcnt(6)
	v_mfma_f32_16x16x32_bf16 v[86:89], v[240:243], v[46:49], v[86:89]
	v_add_f32_e32 v110, 1.0, v110
	v_rcp_f32_e32 v110, v110
	v_mul_f32_e32 v107, 0xbfb8aa3b, v107
	v_mfma_f32_16x16x32_bf16 v[82:85], v[240:243], v[50:53], v[82:85]
	s_nop 0
	v_mul_f32_e32 v110, v147, v110
	v_exp_f32_e32 v110, v110
	s_nop 0
	s_waitcnt lgkmcnt(5)
	v_mfma_f32_16x16x32_bf16 v[86:89], v[244:247], v[58:61], v[86:89]
	v_fma_f32 v195, -v110, v110, 1.0
	v_max_f32_e32 v195, 0, v195
	v_sqrt_f32_e32 v195, v195
	v_mfma_f32_16x16x32_bf16 v[82:85], v[244:247], v[54:57], v[82:85]
	s_nop 0
	v_exp_f32_e32 v107, v107
	v_add_f32_e32 v109, v144, v109
	s_nop 0
	s_waitcnt lgkmcnt(4)
	v_mfma_f32_16x16x32_bf16 v[98:101], v[248:251], v[70:73], v[82:85]
	s_nop 2
	s_nop 0
	v_add_f32_e32 v107, 1.0, v107
	v_rcp_f32_e32 v107, v107
	v_mfma_f32_16x16x32_bf16 v[102:105], v[248:251], v[62:65], v[86:89]
	ds_read_b128 v[236:239], v170 offset:13056
	ds_read_b128 v[240:243], v170 offset:13120
	ds_read_b128 v[244:247], v170 offset:13184
	ds_read_b128 v[248:251], v170 offset:13248
	s_nop 0
	v_mul_f32_e32 v109, 0xbfb8aa3b, v109
	v_exp_f32_e32 v109, v109
	s_nop 0
	s_waitcnt lgkmcnt(7)
	v_mfma_f32_16x16x32_bf16 v[86:89], v[220:223], v[42:45], 0
	v_add_f32_e32 v109, 1.0, v109
	s_nop 1
	v_add_f32_e32 v102, v143, v102
	v_mul_f32_e32 v102, 0xbfb8aa3b, v102
	v_mfma_f32_16x16x32_bf16 v[82:85], v[220:223], v[66:69], 0
	v_exp_f32_e32 v102, v102
	v_rcp_f32_e32 v109, v109
	v_add_f32_e32 v98, v144, v98
	s_nop 0
	s_waitcnt lgkmcnt(6)
	v_mfma_f32_16x16x32_bf16 v[86:89], v[224:227], v[46:49], v[86:89]
	v_add_f32_e32 v102, 1.0, v102
	v_rcp_f32_e32 v102, v102
	v_mul_f32_e32 v98, 0xbfb8aa3b, v98
	v_mfma_f32_16x16x32_bf16 v[82:85], v[224:227], v[50:53], v[82:85]
	s_nop 0
	v_mul_f32_e32 v102, v147, v102
	v_exp_f32_e32 v98, v98
	s_nop 0
	s_waitcnt lgkmcnt(5)
	v_mfma_f32_16x16x32_bf16 v[86:89], v[228:231], v[58:61], v[86:89]
	v_add_f32_e32 v98, 1.0, v98
	v_rcp_f32_e32 v98, v98
	v_add_f32_e32 v99, v144, v99
	v_mfma_f32_16x16x32_bf16 v[82:85], v[228:231], v[54:57], v[82:85]
	s_nop 0
	v_mul_f32_e32 v99, 0xbfb8aa3b, v99
	v_exp_f32_e32 v99, v99
	s_nop 0
	s_waitcnt lgkmcnt(4)
	v_mfma_f32_16x16x32_bf16 v[94:97], v[232:235], v[62:65], v[86:89]
	v_add_f32_e32 v99, 1.0, v99
	v_rcp_f32_e32 v99, v99
	v_add_f32_e32 v101, v144, v101
	v_mfma_f32_16x16x32_bf16 v[90:93], v[232:235], v[70:73], v[82:85]
	s_nop 3
	v_add_f32_e32 v94, v143, v94
	v_mul_f32_e32 v94, 0xbfb8aa3b, v94
	v_exp_f32_e32 v94, v94
	s_nop 0
	s_nop 0
	s_waitcnt lgkmcnt(3)
	v_mfma_f32_16x16x32_bf16 v[86:89], v[236:239], v[42:45], 0
	v_add_f32_e32 v94, 1.0, v94
	v_rcp_f32_e32 v94, v94
	v_add_f32_e32 v90, v144, v90
	v_mfma_f32_16x16x32_bf16 v[82:85], v[236:239], v[66:69], 0
	v_mul_f32_e32 v90, 0xbfb8aa3b, v90
	v_mul_f32_e32 v94, v147, v94
	v_exp_f32_e32 v90, v90
	s_waitcnt lgkmcnt(2)
	v_mfma_f32_16x16x32_bf16 v[86:89], v[240:243], v[46:49], v[86:89]
	v_mul_f32_e32 v101, 0xbfb8aa3b, v101
	v_exp_f32_e32 v101, v101
	v_add_f32_e32 v90, 1.0, v90
	v_mfma_f32_16x16x32_bf16 v[82:85], v[240:243], v[50:53], v[82:85]
	s_nop 0
	v_rcp_f32_e32 v90, v90
	v_add_f32_e32 v101, 1.0, v101
	s_nop 0
	s_waitcnt lgkmcnt(1)
	v_mfma_f32_16x16x32_bf16 v[86:89], v[244:247], v[58:61], v[86:89]
	v_rcp_f32_e32 v206, v101
	v_add_f32_e32 v91, v144, v91
	v_mul_f32_e32 v91, 0xbfb8aa3b, v91
	v_mfma_f32_16x16x32_bf16 v[82:85], v[244:247], v[54:57], v[82:85]
	s_nop 0
	v_exp_f32_e32 v91, v91
	v_add_f32_e32 v93, v144, v93
	s_nop 0
	s_waitcnt lgkmcnt(0)
	v_mfma_f32_16x16x32_bf16 v[86:89], v[248:251], v[62:65], v[86:89]
	v_add_f32_e32 v91, 1.0, v91
	v_rcp_f32_e32 v91, v91
	v_mul_f32_e32 v93, 0xbfb8aa3b, v93
	v_mfma_f32_16x16x32_bf16 v[82:85], v[248:251], v[70:73], v[82:85]
	v_add_u32_e32 v196, s0, v120
	v_cmp_eq_u32_e32 vcc, 0, v196
	s_and_b64 s[46:47], s[40:41], vcc
	v_cndmask_b32_e64 v195, v195, 1.0, s[46:47]
	v_mul_f32_e32 v106, v106, v195
	v_add_u32_e32 v195, 0x8c00, v171
	ds_read2_b32 v[196:197], v195 offset1:132
	v_add_f32_e32 v86, v143, v86
	v_mul_f32_e32 v86, 0xbfb8aa3b, v86
	v_exp_f32_e32 v86, v86
	v_add_f32_e32 v82, v144, v82
	s_waitcnt lgkmcnt(0)
; __device__ __forceinline__ float sigm(float v) { return __builtin_amdgcn_rcpf(1.f + __builtin_amdgcn_exp2f(-LOG2E * v)); }
; __device__ __forceinline__ void lru_unit(Frame& F, int seq, int n) {
;     ...
;             float A[4][4], B[4][4];
; #pragma unroll
;             for (int tt = 0; tt < 4; ++tt)
; #pragma unroll
;                 for (int rg = 0; rg < 4; ++rg) {
;                     const int t = 16 * tt + 4 * tq + rg;
;                     const float r = sigm(ar[tt][rg] + brg), ig = sigm(ai_[tt][rg] + big);
;                     const float av = __builtin_amdgcn_exp2f(r * nsp);
;                     float mult = __builtin_amdgcn_sqrtf(fmaxf(__builtin_fmaf(-av, av, 1.f), 0.f));
;                     if (!smp && (t0 + t) == 0) mult = 1.f;
;                     A[tt][rg] = av; B[tt][rg] = mult * ig * BB[t * 132 + dl];
;                 }
; #pragma unroll
;             for (int tt = 0; tt < 4; ++tt)
; #pragma unroll
;                 for (int rg = 1; rg < 4; ++rg) { B[tt][rg] = A[tt][rg] * B[tt][rg - 1] + B[tt][rg]; A[tt][rg] = A[tt][rg] * A[tt][rg - 1]; }
	v_mul_f32_e32 v195, v106, v196
	v_add_f32_e32 v106, v143, v111
	v_mul_f32_e32 v106, 0xbfb8aa3b, v106
	v_exp_f32_e32 v106, v106
	v_add_f32_e32 v86, 1.0, v86
	v_rcp_f32_e32 v86, v86
	v_mul_f32_e32 v82, 0xbfb8aa3b, v82
	v_add_f32_e32 v106, 1.0, v106
	v_rcp_f32_e32 v106, v106
	v_mul_f32_e32 v86, v147, v86
	v_exp_f32_e32 v82, v82
	v_add_f32_e32 v83, v144, v83
	v_mul_f32_e32 v106, v147, v106
	v_exp_f32_e32 v196, v106
	v_add_f32_e32 v82, 1.0, v82
	v_rcp_f32_e32 v82, v82
	v_mul_f32_e32 v83, 0xbfb8aa3b, v83
	v_fma_f32 v106, -v196, v196, 1.0
	v_max_f32_e32 v106, 0, v106
	v_sqrt_f32_e32 v106, v106
	v_exp_f32_e32 v83, v83
	v_exp_f32_e32 v93, v93
	v_add_f32_e32 v92, v144, v92
	v_mul_f32_e32 v106, v107, v106
	v_add_f32_e32 v107, v144, v108
	v_add_f32_e32 v108, v143, v113
	v_mul_f32_e32 v108, 0xbfb8aa3b, v108
	v_exp_f32_e32 v108, v108
	v_mul_f32_e32 v111, v106, v197
	v_add_f32_e32 v106, v143, v112
	v_mul_f32_e32 v106, 0xbfb8aa3b, v106
	v_add_f32_e32 v108, 1.0, v108
	v_rcp_f32_e32 v108, v108
	v_exp_f32_e32 v106, v106
	v_mul_f32_e32 v107, 0xbfb8aa3b, v107
	v_exp_f32_e32 v107, v107
	v_mul_f32_e32 v108, v147, v108
	v_exp_f32_e32 v199, v108
	v_add_f32_e32 v106, 1.0, v106
	v_rcp_f32_e32 v106, v106
	v_add_f32_e32 v83, 1.0, v83
	v_fma_f32 v108, -v199, v199, 1.0
	v_max_f32_e32 v108, 0, v108
	v_sqrt_f32_e32 v108, v108
	v_mul_f32_e32 v106, v147, v106
	v_exp_f32_e32 v197, v106
	v_add_f32_e32 v107, 1.0, v107
	v_mul_f32_e32 v200, v109, v108
	v_exp_f32_e32 v108, v102
	v_fma_f32 v106, -v197, v197, 1.0
	v_max_f32_e32 v106, 0, v106
	v_rcp_f32_e32 v107, v107
	v_fma_f32 v102, -v108, v108, 1.0
	v_max_f32_e32 v102, 0, v102
	v_sqrt_f32_e32 v102, v102
	v_sqrt_f32_e32 v106, v106
	v_fmac_f32_e32 v111, v196, v195
	v_mul_f32_e32 v92, 0xbfb8aa3b, v92
	v_mul_f32_e32 v98, v98, v102
	v_add_u32_e32 v102, 0xac00, v171
	ds_read2_b32 v[112:113], v102 offset0:64 offset1:196
	v_add_f32_e32 v102, v143, v105
	v_mul_f32_e32 v102, 0xbfb8aa3b, v102
	v_exp_f32_e32 v102, v102
	v_mul_f32_e32 v198, v107, v106
	s_waitcnt lgkmcnt(0)
	v_mul_f32_e32 v109, v98, v112
	v_add_f32_e32 v98, v143, v103
	v_mul_f32_e32 v98, 0xbfb8aa3b, v98
	v_exp_f32_e32 v98, v98
	v_add_f32_e32 v102, 1.0, v102
	v_rcp_f32_e32 v102, v102
	v_add_u32_e32 v106, 0x9000, v171
	v_add_f32_e32 v98, 1.0, v98
	v_rcp_f32_e32 v98, v98
	v_mul_f32_e32 v101, v147, v102
	v_exp_f32_e32 v101, v101
	ds_read2_b32 v[106:107], v106 offset0:8 offset1:140
	v_mul_f32_e32 v98, v147, v98
	v_exp_f32_e32 v203, v98
	v_add_f32_e32 v93, 1.0, v93
	v_mul_f32_e32 v201, v197, v111
	v_exp_f32_e32 v92, v92
	v_fma_f32 v98, -v203, v203, 1.0
	v_max_f32_e32 v98, 0, v98
	v_sqrt_f32_e32 v98, v98
	v_rcp_f32_e32 v210, v93
	s_waitcnt lgkmcnt(0)
	v_fmac_f32_e32 v201, v198, v106
	v_mul_f32_e32 v106, v203, v108
	v_mul_f32_e32 v98, v99, v98
	v_mul_f32_e32 v112, v98, v113
	v_add_f32_e32 v98, v143, v104
	v_exp_f32_e32 v104, v94
	v_exp_f32_e32 v113, v86
	v_mul_f32_e32 v98, 0xbfb8aa3b, v98
	v_exp_f32_e32 v98, v98
	v_fma_f32 v94, -v104, v104, 1.0
	v_max_f32_e32 v94, 0, v94
	v_sqrt_f32_e32 v94, v94
	v_fma_f32 v86, -v113, v113, 1.0
	v_max_f32_e32 v86, 0, v86
	v_sqrt_f32_e32 v86, v86
	v_mul_f32_e32 v90, v90, v94
	v_add_u32_e32 v94, 0xce00, v171
	ds_read2_b32 v[102:103], v94 offset1:132
	v_mul_f32_e32 v86, v82, v86
	v_add_u32_e32 v82, 0xee00, v171
	v_add_f32_e32 v98, 1.0, v98
	v_rcp_f32_e32 v98, v98
	s_waitcnt lgkmcnt(0)
	v_mul_f32_e32 v105, v90, v102
	v_add_f32_e32 v90, v143, v95
	v_mul_f32_e32 v90, 0xbfb8aa3b, v90
	v_exp_f32_e32 v90, v90
	v_add_f32_e32 v99, v144, v100
	v_mul_f32_e32 v98, v147, v98
	v_mul_f32_e32 v99, 0xbfb8aa3b, v99
	v_add_f32_e32 v90, 1.0, v90
	v_rcp_f32_e32 v90, v90
	v_exp_f32_e32 v100, v98
	v_exp_f32_e32 v99, v99
	v_fmac_f32_e32 v112, v203, v109
	v_mul_f32_e32 v90, v147, v90
	v_exp_f32_e32 v90, v90
	v_fma_f32 v98, -v100, v100, 1.0
	v_add_f32_e32 v99, 1.0, v99
	v_max_f32_e32 v98, 0, v98
	v_fma_f32 v94, -v90, v90, 1.0
	v_max_f32_e32 v94, 0, v94
	v_sqrt_f32_e32 v94, v94
	v_rcp_f32_e32 v99, v99
	v_sqrt_f32_e32 v98, v98
	v_add_f32_e32 v92, 1.0, v92
	v_mul_f32_e32 v91, v91, v94
	v_add_f32_e32 v94, v143, v96
	v_mul_f32_e32 v94, 0xbfb8aa3b, v94
	v_exp_f32_e32 v94, v94
	v_mul_f32_e32 v91, v91, v103
	v_mul_f32_e32 v205, v99, v98
	v_add_u32_e32 v98, 0xb000, v171
	v_add_f32_e32 v94, 1.0, v94
	v_rcp_f32_e32 v94, v94
	ds_read2_b32 v[98:99], v98 offset0:72 offset1:204
	v_rcp_f32_e32 v92, v92
	v_fmac_f32_e32 v91, v90, v105
	v_mul_f32_e32 v94, v147, v94
	v_exp_f32_e32 v95, v94
	v_add_u32_e32 v94, 0xd200, v171
	ds_read2_b32 v[102:103], v94 offset0:8 offset1:140
	v_add_f32_e32 v94, v143, v97
	ds_read2_b32 v[96:97], v82 offset0:64 offset1:196
	v_add_f32_e32 v82, v143, v87
	v_mul_f32_e32 v82, 0xbfb8aa3b, v82
	v_exp_f32_e32 v82, v82
	v_rcp_f32_e32 v87, v83
	v_add_f32_e32 v83, v144, v84
	v_mul_f32_e32 v83, 0xbfb8aa3b, v83
	v_add_f32_e32 v82, 1.0, v82
	v_rcp_f32_e32 v82, v82
	v_exp_f32_e32 v83, v83
	v_mul_f32_e32 v94, 0xbfb8aa3b, v94
	v_exp_f32_e32 v94, v94
	v_mul_f32_e32 v82, v147, v82
	v_exp_f32_e32 v204, v82
	v_add_f32_e32 v82, v143, v88
	v_mul_f32_e32 v82, 0xbfb8aa3b, v82
	v_exp_f32_e32 v82, v82
	v_add_f32_e32 v83, 1.0, v83
	v_rcp_f32_e32 v214, v83
	v_add_f32_e32 v83, v144, v85
	v_add_f32_e32 v82, 1.0, v82
	v_rcp_f32_e32 v82, v82
	v_mul_f32_e32 v83, 0xbfb8aa3b, v83
	v_add_f32_e32 v94, 1.0, v94
	v_exp_f32_e32 v83, v83
	v_mul_f32_e32 v82, v147, v82
	v_exp_f32_e32 v207, v82
	v_add_u32_e32 v82, 0xf200, v171
	ds_read2_b32 v[208:209], v82 offset0:72 offset1:204
	v_add_f32_e32 v82, v143, v89
	v_mul_f32_e32 v82, 0xbfb8aa3b, v82
	v_exp_f32_e32 v82, v82
	v_rcp_f32_e32 v94, v94
	v_add_f32_e32 v83, 1.0, v83
	v_rcp_f32_e32 v215, v83
	v_add_f32_e32 v82, 1.0, v82
	v_rcp_f32_e32 v82, v82
	v_mul_f32_e32 v93, v147, v94
	v_mul_f32_e32 v83, v100, v112
	v_exp_f32_e32 v93, v93
	v_mul_f32_e32 v82, v147, v82
	v_exp_f32_e32 v211, v82
	v_fma_f32 v82, -v101, v101, 1.0
	v_max_f32_e32 v82, 0, v82
	v_sqrt_f32_e32 v82, v82
	s_waitcnt lgkmcnt(3)
; __device__ __forceinline__ float sigm(float v) { return __builtin_amdgcn_rcpf(1.f + __builtin_amdgcn_exp2f(-LOG2E * v)); }
; __device__ __forceinline__ void lru_unit(Frame& F, int seq, int n) {
;     ...
;                     const float r = sigm(ar[tt][rg] + brg), ig = sigm(ai_[tt][rg] + big);
;                     const float av = __builtin_amdgcn_exp2f(r * nsp);
;                     float mult = __builtin_amdgcn_sqrtf(fmaxf(__builtin_fmaf(-av, av, 1.f), 0.f));
;                     if (!smp && (t0 + t) == 0) mult = 1.f;
;                     A[tt][rg] = av; B[tt][rg] = mult * ig * BB[t * 132 + dl];
;                 }
; #pragma unroll
;             for (int tt = 0; tt < 4; ++tt)
; #pragma unroll
;                 for (int rg = 1; rg < 4; ++rg) { B[tt][rg] = A[tt][rg] * B[tt][rg - 1] + B[tt][rg]; A[tt][rg] = A[tt][rg] * A[tt][rg - 1]; }
;             float EA[4], EB[4], TA[4], TB[4];
; #pragma unroll
;             for (int tt = 0; tt < 4; ++tt) {
;                 float SA = A[tt][3], SB = B[tt][3];
;                 { const float pA = __shfl_up(SA, 16), pB = __shfl_up(SB, 16); if (tq >= 1) { SB = SA * pB + SB; SA = SA * pA; } }
;                 { const float pA = __shfl_up(SA, 32), pB = __shfl_up(SB, 32); if (tq >= 2) { SB = SA * pB + SB; SA = SA * pA; } }
;                 { const float pA = __shfl_up(SA, 16), pB = __shfl_up(SB, 16); EA[tt] = (tq >= 1) ? pA : 1.f; EB[tt] = (tq >= 1) ? pB : 0.f; }
;                 TA[tt] = __shfl(SA, (lane & 15) + 48); TB[tt] = __shfl(SB, (lane & 15) + 48);
;             }
	v_fmac_f32_e32 v83, v205, v98
	v_mul_f32_e32 v98, v100, v106
	v_mov_b32_e32 v100, v99
	v_mul_f32_e32 v82, v206, v82
	v_pk_mul_f32 v[84:85], v[82:83], v[100:101]
	v_fma_f32 v88, -v93, v93, 1.0
	v_add_f32_e32 v99, v84, v85
	v_fma_f32 v84, -v95, v95, 1.0
	v_max_f32_e32 v84, 0, v84
	v_sqrt_f32_e32 v84, v84
	v_max_f32_e32 v88, 0, v88
	v_sqrt_f32_e32 v88, v88
	v_mul_f32_e32 v82, v90, v104
	s_waitcnt lgkmcnt(2)
	v_mov_b32_e32 v94, v102
	v_mul_f32_e32 v90, v92, v84
	v_mul_f32_e32 v84, v91, v95
	v_pk_fma_f32 v[84:85], v[90:91], v[94:95], v[84:85] op_sel_hi:[1,1,0]
	v_mov_b32_e32 v92, v103
	v_mul_f32_e32 v88, v210, v88
	v_mov_b32_e32 v89, v84
	v_pk_mul_f32 v[88:89], v[88:89], v[92:93]
	s_waitcnt lgkmcnt(1)
	v_mov_b32_e32 v205, v97
	v_add_f32_e32 v90, v88, v89
	v_fma_f32 v88, -v204, v204, 1.0
	v_max_f32_e32 v88, 0, v88
	v_sqrt_f32_e32 v89, v88
	v_mov_b32_e32 v88, v96
	v_mul_f32_e32 v85, v95, v82
	v_mul_f32_e32 v94, v93, v85
	v_pk_mul_f32 v[88:89], v[86:87], v[88:89]
	s_waitcnt lgkmcnt(0)
	v_mov_b32_e32 v206, v208
	v_mul_f32_e32 v86, v97, v89
	v_pk_fma_f32 v[86:87], v[204:205], v[88:89], v[86:87] op_sel_hi:[1,1,0]
	v_fma_f32 v89, -v207, v207, 1.0
	v_max_f32_e32 v89, 0, v89
	v_sqrt_f32_e32 v89, v89
	v_mov_b32_e32 v93, v86
	v_mul_f32_e32 v96, v86, v207
	v_mul_f32_e32 v202, v196, v110
	v_mul_f32_e32 v92, v214, v89
	v_pk_fma_f32 v[92:93], v[92:93], v[206:207], v[96:97] op_sel_hi:[1,1,0]
	v_mul_f32_e32 v197, v197, v202
	v_fma_f32 v93, -v211, v211, 1.0
	v_max_f32_e32 v93, 0, v93
	v_sqrt_f32_e32 v93, v93
	v_mul_f32_e32 v196, v199, v201
	v_mov_b32_e32 v210, v209
	v_mov_b32_e32 v97, v92
	v_mul_f32_e32 v96, v215, v93
	v_fmac_f32_e32 v196, v200, v107
	v_mul_f32_e32 v107, v199, v197
	v_pk_mul_f32 v[96:97], v[96:97], v[210:211]
	v_mul_f32_e32 v100, v101, v98
	v_add_f32_e32 v93, v96, v97
	ds_bpermute_b32 v96, v124, v107
	ds_bpermute_b32 v97, v124, v196
	v_mul_f32_e32 v87, v204, v113
	v_mul_f32_e32 v89, v207, v87
	v_mul_f32_e32 v95, v211, v89
	s_waitcnt lgkmcnt(1)
	v_mul_f32_e32 v96, v107, v96
	s_waitcnt lgkmcnt(0)
	v_fma_f32 v97, v107, v97, v196
	v_cndmask_b32_e64 v96, v96, v107, s[4:5]
	v_cndmask_b32_e64 v97, v97, v196, s[4:5]
	ds_bpermute_b32 v101, v125, v96
	ds_bpermute_b32 v102, v125, v97
	s_waitcnt lgkmcnt(1)
	v_mul_f32_e32 v101, v96, v101
	s_waitcnt lgkmcnt(0)
	v_fma_f32 v102, v96, v102, v97
	v_cndmask_b32_e64 v96, v96, v101, s[6:7]
	v_cndmask_b32_e64 v97, v97, v102, s[6:7]
	ds_bpermute_b32 v101, v124, v96
	ds_bpermute_b32 v199, v164, v96
	ds_bpermute_b32 v96, v124, v100
	ds_bpermute_b32 v102, v124, v97
	ds_bpermute_b32 v200, v164, v97
	ds_bpermute_b32 v97, v124, v99
	s_waitcnt lgkmcnt(5)
	v_cndmask_b32_e64 v101, v101, 1.0, s[4:5]
	s_waitcnt lgkmcnt(3)
	v_mul_f32_e32 v96, v100, v96
	v_cndmask_b32_e64 v96, v96, v100, s[4:5]
	s_waitcnt lgkmcnt(2)
	v_cndmask_b32_e64 v198, v102, 0, s[4:5]
	s_waitcnt lgkmcnt(0)
	v_fma_f32 v97, v100, v97, v99
	v_cndmask_b32_e64 v97, v97, v99, s[4:5]
	ds_bpermute_b32 v102, v125, v96
	ds_bpermute_b32 v103, v125, v97
	v_fmac_f32_e32 v198, v146, v101
	v_fmac_f32_e32 v195, v110, v198
	v_fmac_f32_e32 v111, v202, v198
	s_waitcnt lgkmcnt(1)
	v_mul_f32_e32 v102, v96, v102
	s_waitcnt lgkmcnt(0)
	v_fma_f32 v103, v96, v103, v97
	v_cndmask_b32_e64 v96, v96, v102, s[6:7]
	v_cndmask_b32_e64 v97, v97, v103, s[6:7]
	ds_bpermute_b32 v102, v124, v96
	ds_bpermute_b32 v205, v164, v96
	ds_bpermute_b32 v96, v124, v94
	ds_bpermute_b32 v103, v124, v97
	ds_bpermute_b32 v206, v164, v97
	ds_bpermute_b32 v97, v124, v90
	s_waitcnt lgkmcnt(5)
	v_cndmask_b32_e64 v203, v102, 1.0, s[4:5]
	s_waitcnt lgkmcnt(3)
	v_mul_f32_e32 v96, v94, v96
	v_cndmask_b32_e64 v96, v96, v94, s[4:5]
	ds_bpermute_b32 v102, v125, v96
	s_waitcnt lgkmcnt(1)
	v_fma_f32 v97, v94, v97, v90
	v_cndmask_b32_e64 v97, v97, v90, s[4:5]
	v_cndmask_b32_e64 v204, v103, 0, s[4:5]
	ds_bpermute_b32 v103, v125, v97
	s_waitcnt lgkmcnt(1)
	v_mul_f32_e32 v102, v96, v102
	v_fmac_f32_e32 v201, v197, v198
	v_fmac_f32_e32 v196, v107, v198
	v_fmac_f32_e32 v200, v146, v199
	s_waitcnt lgkmcnt(0)
	v_fma_f32 v103, v96, v103, v97
	v_cndmask_b32_e64 v96, v96, v102, s[6:7]
	v_cndmask_b32_e64 v97, v97, v103, s[6:7]
	ds_bpermute_b32 v102, v124, v96
	ds_bpermute_b32 v209, v164, v96
	ds_bpermute_b32 v96, v124, v95
	ds_bpermute_b32 v103, v124, v97
	ds_bpermute_b32 v210, v164, v97
	ds_bpermute_b32 v97, v124, v93
	s_waitcnt lgkmcnt(5)
	v_cndmask_b32_e64 v207, v102, 1.0, s[4:5]
	s_waitcnt lgkmcnt(3)
	v_mul_f32_e32 v96, v95, v96
	v_cndmask_b32_e64 v96, v96, v95, s[4:5]
	ds_bpermute_b32 v102, v125, v96
	s_waitcnt lgkmcnt(1)
	v_fma_f32 v97, v95, v97, v93
	v_cndmask_b32_e64 v97, v97, v93, s[4:5]
	v_cndmask_b32_e64 v208, v103, 0, s[4:5]
	ds_bpermute_b32 v103, v125, v97
	s_waitcnt lgkmcnt(1)
	v_mul_f32_e32 v102, v96, v102
	v_fmac_f32_e32 v204, v200, v203
	v_fmac_f32_e32 v109, v108, v204
	v_fmac_f32_e32 v112, v106, v204
	s_waitcnt lgkmcnt(0)
; #define GAS __attribute__((address_space(1)))
; __device__ __forceinline__ unsigned pk2(float lo, float hi) { return pg8::cvt_pk_bf16(lo, hi); }
; __device__ __forceinline__ void lru_unit(Frame& F, int seq, int n) {
;     ...
;             const size_t r0 = rowbase + t0 + 4 * tq;
; #pragma unroll
;             for (int tt = 0; tt < 4; ++tt) {
;                 const float hin = EA[tt] * hc + EB[tt];
; #pragma unroll
;                 for (int rg = 0; rg < 4; ++rg) { const float h = A[tt][rg] * hin + B[tt][rg];
;                     const float y = h * bf2f(zc[4 * tt + rg]);
;                     *(GAS unsigned short*)(YAB + (r0 + 16 * tt + rg) * (2 * DM) + dg) = (unsigned short)(pk2(y, 0.f) & 0xffffu); }
;                 hc = TA[tt] * hc + TB[tt];
;             }
; #pragma unroll
;             for (int i = 0; i < 16; ++i) zc[i] = zn[i];
	v_fma_f32 v103, v96, v103, v97
	v_cndmask_b32_e64 v96, v96, v102, s[6:7]
	v_cndmask_b32_e64 v97, v97, v103, s[6:7]
	ds_bpermute_b32 v102, v124, v96
	ds_bpermute_b32 v103, v124, v97
	ds_bpermute_b32 v215, v164, v96
	v_lshlrev_b32_e32 v96, 16, v176
	v_mul_f32_e32 v96, v195, v96
	ds_bpermute_b32 v216, v164, v97
	v_cvt_pk_bf16_f32 v101, v96, v115
	v_lshl_add_u64 v[96:97], v[122:123], 0, s[0:1]
	s_waitcnt lgkmcnt(3)
	v_cndmask_b32_e64 v211, v102, 1.0, s[4:5]
	v_add_co_u32_e32 v102, vcc, s77, v96
	s_waitcnt lgkmcnt(2)
	v_cndmask_b32_e64 v214, v103, 0, s[4:5]
	v_addc_co_u32_e32 v103, vcc, 0, v97, vcc
	global_store_short v[102:103], v101, off offset:-4096
	v_lshlrev_b32_e32 v101, 16, v173
	v_mul_f32_e32 v101, v111, v101
	v_cvt_pk_bf16_f32 v101, v101, v115
	global_store_short v[102:103], v101, off
	s_waitcnt vmcnt(33)
	v_lshlrev_b32_e32 v101, 16, v177
	v_mul_f32_e32 v101, v201, v101
	v_add_co_u32_e32 v102, vcc, s78, v96
	v_cvt_pk_bf16_f32 v101, v101, v115
	v_fmac_f32_e32 v83, v98, v204
	s_nop 0
	v_addc_co_u32_e32 v103, vcc, 0, v97, vcc
	global_store_short v[102:103], v101, off offset:-4096
	s_waitcnt vmcnt(33)
	v_lshlrev_b32_e32 v101, 16, v174
	v_mul_f32_e32 v101, v196, v101
	v_cvt_pk_bf16_f32 v101, v101, v115
	global_store_short v[102:103], v101, off
	s_waitcnt vmcnt(32)
	v_lshlrev_b32_e32 v101, 16, v178
	v_mul_f32_e32 v101, v109, v101
	v_add_co_u32_e32 v102, vcc, s79, v96
	v_cvt_pk_bf16_f32 v101, v101, v115
	s_waitcnt vmcnt(31)
	v_lshlrev_b32_e32 v98, 16, v175
	v_addc_co_u32_e32 v103, vcc, 0, v97, vcc
	global_store_short v[102:103], v101, off offset:-4096
	v_lshlrev_b32_e32 v101, 16, v167
	v_mul_f32_e32 v101, v112, v101
	v_cvt_pk_bf16_f32 v101, v101, v115
	global_store_short v[102:103], v101, off
	v_mul_f32_e32 v83, v83, v98
	v_add_co_u32_e32 v102, vcc, s80, v96
	v_cvt_pk_bf16_f32 v83, v83, v115
	v_fmac_f32_e32 v99, v100, v204
	s_nop 0
	v_addc_co_u32_e32 v103, vcc, 0, v97, vcc
	global_store_short v[102:103], v83, off offset:-4096
	s_waitcnt vmcnt(33)
	v_lshlrev_b32_e32 v83, 16, v172
	v_mul_f32_e32 v83, v99, v83
	v_fmac_f32_e32 v206, v200, v205
	v_cvt_pk_bf16_f32 v83, v83, v115
	v_fmac_f32_e32 v208, v206, v207
	global_store_short v[102:103], v83, off
	v_fmac_f32_e32 v105, v104, v208
	s_waitcnt vmcnt(33)
	v_lshlrev_b32_e32 v83, 16, v168
	v_add_co_u32_e32 v98, vcc, s81, v96
	v_fmac_f32_e32 v91, v82, v208
	s_waitcnt vmcnt(32)
	v_lshlrev_b32_e32 v82, 16, v166
	v_mul_f32_e32 v83, v105, v83
	v_addc_co_u32_e32 v99, vcc, 0, v97, vcc
	v_mul_f32_e32 v82, v91, v82
	v_cvt_pk_bf16_f32 v83, v83, v115
	global_store_short v[98:99], v83, off offset:-4096
	v_cvt_pk_bf16_f32 v82, v82, v115
	global_store_short v[98:99], v82, off
	v_fmac_f32_e32 v84, v85, v208
	s_waitcnt vmcnt(33)
	v_lshlrev_b32_e32 v82, 16, v165
	v_mul_f32_e32 v82, v84, v82
	v_cvt_pk_bf16_f32 v84, v82, v115
	v_add_co_u32_e32 v82, vcc, s82, v96
	v_fmac_f32_e32 v90, v94, v208
	s_nop 0
	v_addc_co_u32_e32 v83, vcc, 0, v97, vcc
	global_store_short v[82:83], v84, off offset:-4096
	s_waitcnt vmcnt(33)
	v_lshlrev_b32_e32 v84, 16, v161
	v_fmac_f32_e32 v210, v206, v209
	v_mul_f32_e32 v84, v90, v84
	v_fmac_f32_e32 v214, v210, v211
	v_cvt_pk_bf16_f32 v84, v84, v115
	global_store_short v[82:83], v84, off
	v_fmac_f32_e32 v88, v113, v214
	s_waitcnt vmcnt(32)
	v_lshlrev_b32_e32 v82, 16, v159
	v_mul_f32_e32 v82, v88, v82
	v_cvt_pk_bf16_f32 v84, v82, v115
	v_add_co_u32_e32 v82, vcc, s83, v96
	v_fmac_f32_e32 v86, v87, v214
	s_nop 0
	v_addc_co_u32_e32 v83, vcc, 0, v97, vcc
	global_store_short v[82:83], v84, off offset:-4096
	v_lshlrev_b32_e32 v84, 16, v154
	v_mul_f32_e32 v84, v86, v84
	v_cvt_pk_bf16_f32 v84, v84, v115
	global_store_short v[82:83], v84, off
	v_fmac_f32_e32 v92, v89, v214
	s_waitcnt vmcnt(33)
	v_lshlrev_b32_e32 v82, 16, v152
	v_mul_f32_e32 v82, v92, v82
	v_cvt_pk_bf16_f32 v84, v82, v115
	v_add_co_u32_e32 v82, vcc, s84, v96
	v_fmac_f32_e32 v93, v95, v214
	s_nop 0
	v_addc_co_u32_e32 v83, vcc, 0, v97, vcc
	global_store_short v[82:83], v84, off
	s_waitcnt vmcnt(33)
	v_lshlrev_b32_e32 v82, 16, v150
	v_mul_f32_e32 v82, v93, v82
	v_cvt_pk_bf16_f32 v84, v82, v115
	v_add_co_u32_e32 v82, vcc, 0x4c433000, v96
	s_waitcnt lgkmcnt(0)
	v_mov_b32_e32 v146, v216
	v_addc_co_u32_e32 v83, vcc, 0, v97, vcc
	s_add_u32 s0, s0, 0x40000
	v_fmac_f32_e32 v146, v210, v215
	s_addc_u32 s1, s1, 0
	s_and_b64 vcc, exec, s[44:45]
	global_store_short v[82:83], v84, off
	s_cbranch_vccnz .LBB0_442
	s_waitcnt vmcnt(31)
	v_mov_b32_e32 v176, v179
	s_waitcnt vmcnt(30)
	v_mov_b32_e32 v173, v180
	s_waitcnt vmcnt(29)
	v_mov_b32_e32 v177, v181
	s_waitcnt vmcnt(28)
	v_mov_b32_e32 v174, v182
	s_waitcnt vmcnt(27)
	v_mov_b32_e32 v178, v183
	s_waitcnt vmcnt(26)
	v_mov_b32_e32 v167, v184
	s_waitcnt vmcnt(25)
	v_mov_b32_e32 v175, v185
	s_waitcnt vmcnt(24)
	v_mov_b32_e32 v172, v186
	s_waitcnt vmcnt(23)
	v_mov_b32_e32 v168, v187
	s_waitcnt vmcnt(22)
	v_mov_b32_e32 v166, v188
	s_waitcnt vmcnt(21)
	v_mov_b32_e32 v165, v189
	s_waitcnt vmcnt(20)
	v_mov_b32_e32 v161, v190
	s_waitcnt vmcnt(19)
	v_mov_b32_e32 v159, v191
	s_waitcnt vmcnt(18)
	v_mov_b32_e32 v154, v192
	s_waitcnt vmcnt(17)
	v_mov_b32_e32 v152, v193
	s_waitcnt vmcnt(16)
	v_mov_b32_e32 v150, v194
	s_branch .LBB0_438
